# MoE down GEMM: WGs with blockIdx bit5 start ~3.4us late (within-XCD phase offset of the Y store bursts)
# baseline (speedup 1.0000x reference)
.LBB0_1139:
	s_cmp_lt_i32 s80, 9
	s_cselect_b64 s[2:3], -1, 0
	s_and_b64 s[4:5], s[2:3], s[0:1]
	s_andn2_b64 vcc, exec, s[4:5]
	s_cbranch_vccnz .LBB0_1166
	s_bitcmp1_b32 s69, 5
	s_cbranch_scc0 .Lst8_done
	s_movk_i32 s98, 4
.Lst8_loop:
	s_sleep 32
	s_sub_u32 s98, s98, 1
	s_cmp_lg_u32 s98, 0
	s_cbranch_scc1 .Lst8_loop
.Lst8_done:
	s_cmpk_gt_i32 s69, 0x7ff
	v_readfirstlane_b32 s2, v193
	s_cbranch_scc1 .LBB0_1166
	s_ashr_i32 s33, s69, 31
	s_lshr_b32 s0, s33, 29
	s_add_i32 s7, s69, s0
	s_and_b32 s0, s7, -8
	s_sub_i32 s3, s69, s0
	s_cmp_gt_i32 s3, -1
	s_cbranch_scc0 .LBB0_1143
	s_lshl_b32 s6, s3, 8
	s_ashr_i32 s0, s7, 3
	s_cbranch_execz .LBB0_1144
	s_branch .LBB0_1145
